# FoX work queue: after the own-queue ticket fails, one parallel sc1 load of all 8 queue counters picks the first non-exhausted queue (or exits) instead of up to 7 serial atomics
# speedup vs baseline: 1.0025x; 1.0025x over previous
; __device__ __forceinline__ int mk_tid() { int t = threadIdx.x; asm volatile("" : "+v"(t)); return t; }
;   __device__ __forceinline__ bool next(int i,AttnUnit&u)const{ if(i>=4)return false; const int s=vcu&7; u.bh=vcu>>3; u.qb=(i==0)?s:(i==1)?15-s:(i==2)?16+s:31-s; return true; }
;     __device__ __forceinline__ bool next(int i, pg8::Unit& u) const { return so.next(i, u); }
;     __device__ __forceinline__ bool next(int i, pg8::Unit& u) const { if (i >= 4) return false; u.pm = vcu >> 2; u.pn = i * 4 + (vcu & 3); return true; }
;   __device__ __forceinline__ bool next(int,AttnUnit&u)const{
;     if(mk_tid()==0){ int got=-1;
;       for(int k=0;k<8&&got<0;++k){ const int q=(xl+k)&7; const int j=(int)__hip_atomic_fetch_add(ctr+q*64,1u,__ATOMIC_RELAXED,__HIP_MEMORY_SCOPE_AGENT); if(j<128)got=q*128+j; }
;       *slot=got; }
;     __syncthreads(); const int g=*slot; if(g<0)return false; const int q=g>>7,j=g&127; u.bh=q*4+(j&3); u.qb=31-(j>>2); return true; }
.LBB9_241:
	s_or_b64 exec, exec, s[12:13]
	s_waitcnt vmcnt(0)
	v_readfirstlane_b32 s5, v3
	s_add_i32 s10, s2, 1
	s_cmp_gt_u32 s2, 6
	v_add_u32_e32 v2, s5, v2
	v_lshl_add_u32 v3, s4, 7, v2
	s_movk_i32 s4, 0x80
	v_cmp_gt_i32_e32 vcc, s4, v2
	s_cselect_b64 s[4:5], -1, 0
	s_mov_b32 s2, s10
	v_cndmask_b32_e32 v0, v0, v3, vcc
	v_cmp_lt_i32_e32 vcc, -1, v0
	s_or_b64 s[4:5], s[4:5], vcc
	s_and_b64 s[4:5], exec, s[4:5]
	s_or_b64 s[8:9], s[4:5], s[8:9]
	s_andn2_b64 exec, exec, s[8:9]
	s_cbranch_execz .LBB9_244
	s_cmp_lg_u32 s2, 1
	s_cbranch_scc1 .Lfq_cont
	s_mov_b64 s[10:11], exec
	s_mov_b64 exec, 0xff
	v_add_u32_e32 v2, s90, v244
	v_and_b32_e32 v2, 7, v2
	v_lshlrev_b32_e32 v2, 8, v2
	global_load_dword v3, v2, s[18:19] sc1
	s_waitcnt vmcnt(0)
	v_cmp_gt_u32_e32 vcc, 0x80, v3
	s_mov_b64 exec, s[10:11]
	s_and_b32 s4, vcc_lo, 0xfe
	s_ff1_i32_b32 s5, s4
	s_cmp_lt_i32 s5, 0
	s_cbranch_scc1 .LBB9_244
	s_mov_b32 s2, s5
.Lfq_cont:
.LBB9_242:
	s_mov_b64 s[10:11], exec
	v_mbcnt_lo_u32_b32 v2, s10, 0
	s_add_i32 s4, s90, s2
	v_mbcnt_hi_u32_b32 v2, s11, v2
	s_and_b32 s4, s4, 7
	v_cmp_eq_u32_e32 vcc, 0, v2
	s_and_saveexec_b64 s[12:13], vcc
	s_cbranch_execz .LBB9_241
	s_lshl_b32 s5, s4, 8
	s_bcnt1_i32_b64 s10, s[10:11]
	v_mov_b32_e32 v3, s5
	v_mov_b32_e32 v4, s10
	global_atomic_add v3, v3, v4, s[18:19] sc0
	s_branch .LBB9_241
